# the grid barrier behind the last layer's LayerNorm is skipped (waves end right after their rows; it ordered nothing)
# baseline (speedup 1.0000x reference)
; template <class T> __device__ __forceinline__ T launder(T p) { asm volatile("" : "+s"(p)); return p; }
; __global__ void __launch_bounds__(512, 2) mega(Params p_unused) {
;     ...
;     xcd_barrier(kp0, st);
;     if (PH_MASK & 1024) {
;       const KP kp = launder(kp0);
;       phase_ln(kp->out + O_Y, kp->ln2_g + l * 1024, kp->ln2_b + l * 1024, l == 0 ? (bf16_t*)(kp->ws + W_XBF) : nullptr, l == 0 ? ALPHA : 1.0f, (const float*)(kp->ws + W_PART), 8, l == 1);
;     }
;     xcd_barrier(kp0, st);
;   }
.Lln2_end:
	v_readlane_b32 s0, v255, 22
	s_nop 0
	s_cmp_lg_u32 s0, 1
	s_cbranch_scc1 .Lln2_cont
	s_endpgm
